# gemm1 K-loop rewritten: LDS-DMA global_load_lds + XOR-swizzled unpadded LDS tiles, 4 fragment buffers, barrier rotated mid-MFMA-stream
# speedup vs baseline: 1.0477x; 1.0477x over previous
.LBB0_513:
	v_mov_b32_e32 v0, v1
	s_and_b32 s28, s25, 0x1f80
	v_mbcnt_lo_u32_b32 v0, -1, v0
	v_mbcnt_hi_u32_b32 v0, -1, v0
	v_add_u32_e32 v88, s80, v0
	s_and_b32 s27, s24, 0xffffff80
	s_waitcnt lgkmcnt(0)
	v_ashrrev_i32_e32 v2, 3, v88
	v_lshlrev_b32_e32 v89, 3, v88
	v_and_b32_e32 v34, 56, v89
	v_add_u32_e32 v0, s28, v2
	v_lshl_or_b32 v0, v0, 10, v34
	v_lshl_add_u64 v[72:73], v[0:1], 1, s[4:5]
	v_add_u32_e32 v0, s27, v2
	v_lshl_or_b32 v0, v0, 10, v34
	v_lshl_add_u64 v[74:75], v[0:1], 1, s[72:73]
	v_add_co_u32_e32 v76, vcc, s18, v74
	s_mov_b32 s20, 0x20000
	s_nop 0
	v_addc_co_u32_e32 v77, vcc, 0, v75, vcc
	v_add_co_u32_e32 v78, vcc, s20, v74
	v_mul_lo_u32 v35, v2, s31
	s_nop 0
	v_addc_co_u32_e32 v79, vcc, 0, v75, vcc
	v_add_co_u32_e32 v80, vcc, s10, v74
	s_nop 0
	s_nop 0
	v_addc_co_u32_e32 v81, vcc, 0, v75, vcc
	s_nop 0
	s_nop 0
	s_nop 0
	v_add_co_u32_e32 v82, vcc, s18, v72
	v_add_lshl_u32 v91, v35, v34, 1
	s_nop 0
	v_addc_co_u32_e32 v83, vcc, 0, v73, vcc
	v_add_co_u32_e32 v84, vcc, s20, v72
	s_nop 0
	s_nop 0
	v_addc_co_u32_e32 v85, vcc, 0, v73, vcc
	v_add_co_u32_e32 v86, vcc, s10, v72
	s_nop 0
	s_nop 0
	v_addc_co_u32_e32 v87, vcc, 0, v73, vcc
	s_nop 0
	s_waitcnt lgkmcnt(0)
	s_barrier
	v_and_b32_e32 v0, 31, v88
	s_movk_i32 s20, 0x90
	v_add_u32_e32 v92, 0xd800, v91
	v_ashrrev_i32_e32 v2, 1, v88
	v_and_b32_e32 v90, 0xffffffc0, v2
	v_bfe_u32 v102, v88, 4, 3
	v_lshlrev_b32_e32 v102, 4, v102
	v_xor_b32_e32 v74, v102, v74
	v_xor_b32_e32 v76, v102, v76
	v_xor_b32_e32 v78, v102, v78
	v_xor_b32_e32 v80, v102, v80
	v_xor_b32_e32 v72, v102, v72
	v_xor_b32_e32 v82, v102, v82
	v_xor_b32_e32 v84, v102, v84
	v_xor_b32_e32 v86, v102, v86
	v_bfe_u32 v102, v88, 5, 1
	v_bfe_u32 v103, v88, 1, 3
	v_xor_b32_e32 v102, v102, v103
	v_lshlrev_b32_e32 v102, 4, v102
	v_lshrrev_b32_e32 v103, 1, v88
	v_and_b32_e32 v103, 64, v103
	v_and_b32_e32 v104, 31, v88
	v_or_b32_e32 v103, v103, v104
	v_lshl_or_b32 v94, v103, 7, v102
	v_and_b32_e32 v103, 0x5f, v88
	v_lshl_or_b32 v98, v103, 7, v102
	v_add_u32_e32 v98, 0x4000, v98
	v_xor_b32_e32 v95, 0x20, v94
	v_xor_b32_e32 v99, 0x20, v98
	v_xor_b32_e32 v96, 0x40, v94
	v_xor_b32_e32 v100, 0x40, v98
	v_xor_b32_e32 v97, 0x60, v94
	v_xor_b32_e32 v101, 0x60, v98
	v_mov_b32_e32 v214, 0x80
	v_mov_b32_e32 v215, 0
	s_lshl_b32 vcc_lo, s80, 4
	v_mov_b32_e32 v2, 0
	v_mov_b32_e32 v3, 0
	v_mov_b32_e32 v4, 0
	v_mov_b32_e32 v5, 0
	v_mov_b32_e32 v6, 0
	v_mov_b32_e32 v7, 0
	v_mov_b32_e32 v8, 0
	v_mov_b32_e32 v9, 0
	v_mov_b32_e32 v10, 0
	v_mov_b32_e32 v11, 0
	v_mov_b32_e32 v12, 0
	v_mov_b32_e32 v13, 0
	v_mov_b32_e32 v14, 0
	v_mov_b32_e32 v15, 0
	v_mov_b32_e32 v16, 0
	v_mov_b32_e32 v17, 0
	v_mov_b32_e32 v18, 0
	v_mov_b32_e32 v19, 0
	v_mov_b32_e32 v20, 0
	v_mov_b32_e32 v21, 0
	v_mov_b32_e32 v22, 0
	v_mov_b32_e32 v23, 0
	v_mov_b32_e32 v24, 0
	v_mov_b32_e32 v25, 0
	v_mov_b32_e32 v26, 0
	v_mov_b32_e32 v27, 0
	v_mov_b32_e32 v28, 0
	v_mov_b32_e32 v29, 0
	v_mov_b32_e32 v30, 0
	v_mov_b32_e32 v31, 0
	v_mov_b32_e32 v32, 0
	v_mov_b32_e32 v33, 0
	v_mov_b32_e32 v34, 0
	v_mov_b32_e32 v35, 0
	v_mov_b32_e32 v36, 0
	v_mov_b32_e32 v37, 0
	v_mov_b32_e32 v38, 0
	v_mov_b32_e32 v39, 0
	v_mov_b32_e32 v40, 0
	v_mov_b32_e32 v41, 0
	v_mov_b32_e32 v42, 0
	v_mov_b32_e32 v43, 0
	v_mov_b32_e32 v44, 0
	v_mov_b32_e32 v45, 0
	v_mov_b32_e32 v46, 0
	v_mov_b32_e32 v47, 0
	v_mov_b32_e32 v48, 0
	v_mov_b32_e32 v49, 0
	v_mov_b32_e32 v50, 0
	v_mov_b32_e32 v51, 0
	v_mov_b32_e32 v52, 0
	v_mov_b32_e32 v53, 0
	v_mov_b32_e32 v54, 0
	v_mov_b32_e32 v55, 0
	v_mov_b32_e32 v56, 0
	v_mov_b32_e32 v57, 0
	v_mov_b32_e32 v58, 0
	v_mov_b32_e32 v59, 0
	v_mov_b32_e32 v60, 0
	v_mov_b32_e32 v61, 0
	v_mov_b32_e32 v62, 0
	v_mov_b32_e32 v63, 0
	v_mov_b32_e32 v64, 0
	v_mov_b32_e32 v65, 0
	s_mov_b32 m0, vcc_lo
	s_nop 0
	global_load_lds_dwordx4 v[74:75], off
	s_add_u32 m0, vcc_lo, 0x1000
	s_nop 0
	global_load_lds_dwordx4 v[76:77], off
	s_add_u32 m0, vcc_lo, 0x2000
	s_nop 0
	global_load_lds_dwordx4 v[78:79], off
	s_add_u32 m0, vcc_lo, 0x3000
	s_nop 0
	global_load_lds_dwordx4 v[80:81], off
	s_add_u32 m0, vcc_lo, 0x4000
	s_nop 0
	global_load_lds_dwordx4 v[72:73], off
	s_add_u32 m0, vcc_lo, 0x5000
	s_nop 0
	global_load_lds_dwordx4 v[82:83], off
	s_add_u32 m0, vcc_lo, 0x6000
	s_nop 0
	global_load_lds_dwordx4 v[84:85], off
	s_add_u32 m0, vcc_lo, 0x7000
	s_nop 0
	global_load_lds_dwordx4 v[86:87], off
	v_lshl_add_u64 v[74:75], v[74:75], 0, v[214:215]
	v_lshl_add_u64 v[76:77], v[76:77], 0, v[214:215]
	v_lshl_add_u64 v[78:79], v[78:79], 0, v[214:215]
	v_lshl_add_u64 v[80:81], v[80:81], 0, v[214:215]
	v_lshl_add_u64 v[72:73], v[72:73], 0, v[214:215]
	v_lshl_add_u64 v[82:83], v[82:83], 0, v[214:215]
	v_lshl_add_u64 v[84:85], v[84:85], 0, v[214:215]
	v_lshl_add_u64 v[86:87], v[86:87], 0, v[214:215]
	s_add_u32 m0, vcc_lo, 0x8000
	s_nop 0
	global_load_lds_dwordx4 v[74:75], off
	s_add_u32 m0, vcc_lo, 0x9000
	s_nop 0
	global_load_lds_dwordx4 v[76:77], off
	s_add_u32 m0, vcc_lo, 0xa000
	s_nop 0
	global_load_lds_dwordx4 v[78:79], off
	s_add_u32 m0, vcc_lo, 0xb000
	s_nop 0
	global_load_lds_dwordx4 v[80:81], off
	s_add_u32 m0, vcc_lo, 0xc000
	s_nop 0
	global_load_lds_dwordx4 v[72:73], off
	s_add_u32 m0, vcc_lo, 0xd000
	s_nop 0
	global_load_lds_dwordx4 v[82:83], off
	s_add_u32 m0, vcc_lo, 0xe000
	s_nop 0
	global_load_lds_dwordx4 v[84:85], off
	s_add_u32 m0, vcc_lo, 0xf000
	s_nop 0
	global_load_lds_dwordx4 v[86:87], off
	v_lshl_add_u64 v[74:75], v[74:75], 0, v[214:215]
	v_lshl_add_u64 v[76:77], v[76:77], 0, v[214:215]
	v_lshl_add_u64 v[78:79], v[78:79], 0, v[214:215]
	v_lshl_add_u64 v[80:81], v[80:81], 0, v[214:215]
	v_lshl_add_u64 v[72:73], v[72:73], 0, v[214:215]
	v_lshl_add_u64 v[82:83], v[82:83], 0, v[214:215]
	v_lshl_add_u64 v[84:85], v[84:85], 0, v[214:215]
	v_lshl_add_u64 v[86:87], v[86:87], 0, v[214:215]
	s_mov_b32 vcc_hi, 7
	s_waitcnt vmcnt(8)
	s_barrier
	ds_read_b128 v[166:169], v94
	ds_read_b128 v[170:173], v98
	ds_read_b128 v[174:177], v98 offset:4096
	ds_read_b128 v[178:181], v94 offset:4096
	ds_read_b128 v[182:185], v95
	ds_read_b128 v[188:191], v99
	ds_read_b128 v[192:195], v99 offset:4096
	ds_read_b128 v[206:209], v95 offset:4096
	s_waitcnt lgkmcnt(6)
	v_mfma_f32_32x32x16_bf16 v[50:65], v[166:169], v[170:173], v[50:65]
	ds_read_b128 v[236:239], v96
	s_waitcnt lgkmcnt(6)
	v_mfma_f32_32x32x16_bf16 v[34:49], v[166:169], v[174:177], v[34:49]
	ds_read_b128 v[240:243], v100
	s_waitcnt lgkmcnt(6)
	v_mfma_f32_32x32x16_bf16 v[18:33], v[178:181], v[170:173], v[18:33]
	ds_read_b128 v[244:247], v100 offset:4096
	v_mfma_f32_32x32x16_bf16 v[2:17], v[178:181], v[174:177], v[2:17]
	ds_read_b128 v[248:251], v96 offset:4096
	s_waitcnt lgkmcnt(6)
	v_mfma_f32_32x32x16_bf16 v[50:65], v[182:185], v[188:191], v[50:65]
	ds_read_b128 v[126:129], v97
	s_waitcnt lgkmcnt(6)
	v_mfma_f32_32x32x16_bf16 v[34:49], v[182:185], v[192:195], v[34:49]
	ds_read_b128 v[130:133], v101
	s_waitcnt lgkmcnt(6)
	v_mfma_f32_32x32x16_bf16 v[18:33], v[206:209], v[188:191], v[18:33]
	ds_read_b128 v[210:213], v101 offset:4096
	v_mfma_f32_32x32x16_bf16 v[2:17], v[206:209], v[192:195], v[2:17]
	ds_read_b128 v[222:225], v97 offset:4096
	s_waitcnt vmcnt(0) lgkmcnt(0)
	s_barrier
.Lg_gemm1_loop:
	v_mfma_f32_32x32x16_bf16 v[50:65], v[236:239], v[240:243], v[50:65]
	s_mov_b32 m0, vcc_lo
	ds_read_b128 v[166:169], v94 offset:32768
	global_load_lds_dwordx4 v[74:75], off
	v_mfma_f32_32x32x16_bf16 v[34:49], v[236:239], v[244:247], v[34:49]
	s_add_u32 m0, vcc_lo, 0x1000
	ds_read_b128 v[170:173], v98 offset:32768
	global_load_lds_dwordx4 v[76:77], off
	v_mfma_f32_32x32x16_bf16 v[18:33], v[248:251], v[240:243], v[18:33]
	s_add_u32 m0, vcc_lo, 0x2000
	ds_read_b128 v[174:177], v98 offset:36864
	global_load_lds_dwordx4 v[78:79], off
	v_mfma_f32_32x32x16_bf16 v[2:17], v[248:251], v[244:247], v[2:17]
	s_add_u32 m0, vcc_lo, 0x3000
	ds_read_b128 v[178:181], v94 offset:36864
	global_load_lds_dwordx4 v[80:81], off
	v_mfma_f32_32x32x16_bf16 v[50:65], v[126:129], v[130:133], v[50:65]
	s_add_u32 m0, vcc_lo, 0x4000
	ds_read_b128 v[182:185], v95 offset:32768
	global_load_lds_dwordx4 v[72:73], off
	v_mfma_f32_32x32x16_bf16 v[34:49], v[126:129], v[210:213], v[34:49]
	s_add_u32 m0, vcc_lo, 0x5000
	ds_read_b128 v[188:191], v99 offset:32768
	global_load_lds_dwordx4 v[82:83], off
	v_mfma_f32_32x32x16_bf16 v[18:33], v[222:225], v[130:133], v[18:33]
	s_add_u32 m0, vcc_lo, 0x6000
	ds_read_b128 v[192:195], v99 offset:36864
	global_load_lds_dwordx4 v[84:85], off
	v_mfma_f32_32x32x16_bf16 v[2:17], v[222:225], v[210:213], v[2:17]
	s_add_u32 m0, vcc_lo, 0x7000
	ds_read_b128 v[206:209], v95 offset:36864
	global_load_lds_dwordx4 v[86:87], off
	s_waitcnt lgkmcnt(6)
	v_mfma_f32_32x32x16_bf16 v[50:65], v[166:169], v[170:173], v[50:65]
	ds_read_b128 v[236:239], v96 offset:32768
	v_lshl_add_u64 v[74:75], v[74:75], 0, v[214:215]
	v_lshl_add_u64 v[76:77], v[76:77], 0, v[214:215]
	v_lshl_add_u64 v[78:79], v[78:79], 0, v[214:215]
	v_lshl_add_u64 v[80:81], v[80:81], 0, v[214:215]
	v_lshl_add_u64 v[72:73], v[72:73], 0, v[214:215]
	v_lshl_add_u64 v[82:83], v[82:83], 0, v[214:215]
	v_lshl_add_u64 v[84:85], v[84:85], 0, v[214:215]
	v_lshl_add_u64 v[86:87], v[86:87], 0, v[214:215]
	s_waitcnt lgkmcnt(6)
	v_mfma_f32_32x32x16_bf16 v[34:49], v[166:169], v[174:177], v[34:49]
	ds_read_b128 v[240:243], v100 offset:32768
	s_waitcnt lgkmcnt(6)
	v_mfma_f32_32x32x16_bf16 v[18:33], v[178:181], v[170:173], v[18:33]
	ds_read_b128 v[244:247], v100 offset:36864
	v_mfma_f32_32x32x16_bf16 v[2:17], v[178:181], v[174:177], v[2:17]
	ds_read_b128 v[248:251], v96 offset:36864
	s_waitcnt lgkmcnt(6)
	v_mfma_f32_32x32x16_bf16 v[50:65], v[182:185], v[188:191], v[50:65]
	ds_read_b128 v[126:129], v97 offset:32768
	s_waitcnt lgkmcnt(6)
	v_mfma_f32_32x32x16_bf16 v[34:49], v[182:185], v[192:195], v[34:49]
	ds_read_b128 v[130:133], v101 offset:32768
	s_waitcnt lgkmcnt(6)
	v_mfma_f32_32x32x16_bf16 v[18:33], v[206:209], v[188:191], v[18:33]
	ds_read_b128 v[210:213], v101 offset:36864
	v_mfma_f32_32x32x16_bf16 v[2:17], v[206:209], v[192:195], v[2:17]
	ds_read_b128 v[222:225], v97 offset:36864
	s_waitcnt vmcnt(0) lgkmcnt(0)
	s_barrier
	v_mfma_f32_32x32x16_bf16 v[50:65], v[236:239], v[240:243], v[50:65]
	s_add_u32 m0, vcc_lo, 0x8000
	ds_read_b128 v[166:169], v94
	global_load_lds_dwordx4 v[74:75], off
	v_mfma_f32_32x32x16_bf16 v[34:49], v[236:239], v[244:247], v[34:49]
	s_add_u32 m0, vcc_lo, 0x9000
	ds_read_b128 v[170:173], v98
	global_load_lds_dwordx4 v[76:77], off
	v_mfma_f32_32x32x16_bf16 v[18:33], v[248:251], v[240:243], v[18:33]
	s_add_u32 m0, vcc_lo, 0xa000
	ds_read_b128 v[174:177], v98 offset:4096
	global_load_lds_dwordx4 v[78:79], off
	v_mfma_f32_32x32x16_bf16 v[2:17], v[248:251], v[244:247], v[2:17]
	s_add_u32 m0, vcc_lo, 0xb000
	ds_read_b128 v[178:181], v94 offset:4096
	global_load_lds_dwordx4 v[80:81], off
	v_mfma_f32_32x32x16_bf16 v[50:65], v[126:129], v[130:133], v[50:65]
	s_add_u32 m0, vcc_lo, 0xc000
	ds_read_b128 v[182:185], v95
	global_load_lds_dwordx4 v[72:73], off
	v_mfma_f32_32x32x16_bf16 v[34:49], v[126:129], v[210:213], v[34:49]
	s_add_u32 m0, vcc_lo, 0xd000
	ds_read_b128 v[188:191], v99
	global_load_lds_dwordx4 v[82:83], off
	v_mfma_f32_32x32x16_bf16 v[18:33], v[222:225], v[130:133], v[18:33]
	s_add_u32 m0, vcc_lo, 0xe000
	ds_read_b128 v[192:195], v99 offset:4096
	global_load_lds_dwordx4 v[84:85], off
	v_mfma_f32_32x32x16_bf16 v[2:17], v[222:225], v[210:213], v[2:17]
	s_add_u32 m0, vcc_lo, 0xf000
	ds_read_b128 v[206:209], v95 offset:4096
	global_load_lds_dwordx4 v[86:87], off
	s_waitcnt lgkmcnt(6)
	v_mfma_f32_32x32x16_bf16 v[50:65], v[166:169], v[170:173], v[50:65]
	ds_read_b128 v[236:239], v96
	v_lshl_add_u64 v[74:75], v[74:75], 0, v[214:215]
	v_lshl_add_u64 v[76:77], v[76:77], 0, v[214:215]
	v_lshl_add_u64 v[78:79], v[78:79], 0, v[214:215]
	v_lshl_add_u64 v[80:81], v[80:81], 0, v[214:215]
	v_lshl_add_u64 v[72:73], v[72:73], 0, v[214:215]
	v_lshl_add_u64 v[82:83], v[82:83], 0, v[214:215]
	v_lshl_add_u64 v[84:85], v[84:85], 0, v[214:215]
	v_lshl_add_u64 v[86:87], v[86:87], 0, v[214:215]
	s_waitcnt lgkmcnt(6)
	v_mfma_f32_32x32x16_bf16 v[34:49], v[166:169], v[174:177], v[34:49]
	ds_read_b128 v[240:243], v100
	s_waitcnt lgkmcnt(6)
	v_mfma_f32_32x32x16_bf16 v[18:33], v[178:181], v[170:173], v[18:33]
	ds_read_b128 v[244:247], v100 offset:4096
	v_mfma_f32_32x32x16_bf16 v[2:17], v[178:181], v[174:177], v[2:17]
	ds_read_b128 v[248:251], v96 offset:4096
	s_waitcnt lgkmcnt(6)
	v_mfma_f32_32x32x16_bf16 v[50:65], v[182:185], v[188:191], v[50:65]
	ds_read_b128 v[126:129], v97
	s_waitcnt lgkmcnt(6)
	v_mfma_f32_32x32x16_bf16 v[34:49], v[182:185], v[192:195], v[34:49]
	ds_read_b128 v[130:133], v101
	s_waitcnt lgkmcnt(6)
	v_mfma_f32_32x32x16_bf16 v[18:33], v[206:209], v[188:191], v[18:33]
	ds_read_b128 v[210:213], v101 offset:4096
	v_mfma_f32_32x32x16_bf16 v[2:17], v[206:209], v[192:195], v[2:17]
	ds_read_b128 v[222:225], v97 offset:4096
	s_waitcnt vmcnt(0) lgkmcnt(0)
	s_barrier
	s_sub_u32 vcc_hi, vcc_hi, 1
	s_cmp_lg_u32 vcc_hi, 0
	s_cbranch_scc1 .Lg_gemm1_loop
	v_mfma_f32_32x32x16_bf16 v[50:65], v[236:239], v[240:243], v[50:65]
	ds_read_b128 v[166:169], v94 offset:32768
	v_mfma_f32_32x32x16_bf16 v[34:49], v[236:239], v[244:247], v[34:49]
	ds_read_b128 v[170:173], v98 offset:32768
	v_mfma_f32_32x32x16_bf16 v[18:33], v[248:251], v[240:243], v[18:33]
	ds_read_b128 v[174:177], v98 offset:36864
	v_mfma_f32_32x32x16_bf16 v[2:17], v[248:251], v[244:247], v[2:17]
	ds_read_b128 v[178:181], v94 offset:36864
	v_mfma_f32_32x32x16_bf16 v[50:65], v[126:129], v[130:133], v[50:65]
	ds_read_b128 v[182:185], v95 offset:32768
	v_mfma_f32_32x32x16_bf16 v[34:49], v[126:129], v[210:213], v[34:49]
	ds_read_b128 v[188:191], v99 offset:32768
	v_mfma_f32_32x32x16_bf16 v[18:33], v[222:225], v[130:133], v[18:33]
	ds_read_b128 v[192:195], v99 offset:36864
	v_mfma_f32_32x32x16_bf16 v[2:17], v[222:225], v[210:213], v[2:17]
	ds_read_b128 v[206:209], v95 offset:36864
	s_waitcnt lgkmcnt(6)
	v_mfma_f32_32x32x16_bf16 v[50:65], v[166:169], v[170:173], v[50:65]
	ds_read_b128 v[236:239], v96 offset:32768
	s_waitcnt lgkmcnt(6)
	v_mfma_f32_32x32x16_bf16 v[34:49], v[166:169], v[174:177], v[34:49]
	ds_read_b128 v[240:243], v100 offset:32768
	s_waitcnt lgkmcnt(6)
	v_mfma_f32_32x32x16_bf16 v[18:33], v[178:181], v[170:173], v[18:33]
	ds_read_b128 v[244:247], v100 offset:36864
	v_mfma_f32_32x32x16_bf16 v[2:17], v[178:181], v[174:177], v[2:17]
	ds_read_b128 v[248:251], v96 offset:36864
	s_waitcnt lgkmcnt(6)
	v_mfma_f32_32x32x16_bf16 v[50:65], v[182:185], v[188:191], v[50:65]
	ds_read_b128 v[126:129], v97 offset:32768
	s_waitcnt lgkmcnt(6)
	v_mfma_f32_32x32x16_bf16 v[34:49], v[182:185], v[192:195], v[34:49]
	ds_read_b128 v[130:133], v101 offset:32768
	s_waitcnt lgkmcnt(6)
	v_mfma_f32_32x32x16_bf16 v[18:33], v[206:209], v[188:191], v[18:33]
	ds_read_b128 v[210:213], v101 offset:36864
	v_mfma_f32_32x32x16_bf16 v[2:17], v[206:209], v[192:195], v[2:17]
	ds_read_b128 v[222:225], v97 offset:36864
	s_waitcnt lgkmcnt(6)
	v_mfma_f32_32x32x16_bf16 v[50:65], v[236:239], v[240:243], v[50:65]
	s_waitcnt lgkmcnt(5)
	v_mfma_f32_32x32x16_bf16 v[34:49], v[236:239], v[244:247], v[34:49]
	s_waitcnt lgkmcnt(4)
	v_mfma_f32_32x32x16_bf16 v[18:33], v[248:251], v[240:243], v[18:33]
	v_mfma_f32_32x32x16_bf16 v[2:17], v[248:251], v[244:247], v[2:17]
	s_waitcnt lgkmcnt(2)
	v_mfma_f32_32x32x16_bf16 v[50:65], v[126:129], v[130:133], v[50:65]
	s_waitcnt lgkmcnt(1)
	v_mfma_f32_32x32x16_bf16 v[34:49], v[126:129], v[210:213], v[34:49]
	s_waitcnt lgkmcnt(0)
	v_mfma_f32_32x32x16_bf16 v[18:33], v[222:225], v[130:133], v[18:33]
	v_mfma_f32_32x32x16_bf16 v[2:17], v[222:225], v[210:213], v[2:17]
	s_nop 7
	s_nop 7
	s_cmpk_lt_u32 s28, 0x400
	s_movk_i32 s29, 0x400
	s_barrier
	s_cbranch_scc1 .LBB0_522
	s_cmpk_gt_u32 s28, 0xdff
	s_mov_b64 s[22:23], -1
	s_cbranch_scc0 .LBB0_520
	s_cmpk_gt_u32 s28, 0x13ff
	s_mov_b64 s[20:21], -1
	s_cbranch_scc0 .LBB0_517
	s_add_i32 s30, s28, 0xffffec00
	s_mov_b64 s[20:21], 0
